# nt hint on the write-only AK/AV f32 output stores of the odin epilogue (never re-read in the kernel)
# speedup vs baseline: 1.0031x; 1.0031x over previous
.Lodin4_kseg:
	s_cmp_ge_u32 s11, 0x2000
	s_cbranch_scc1 .Lodin4_kbase
	s_lshl_b32 s8, s7, 12
	s_lshl_b32 s9, s6, 2
	s_add_u32 s8, s8, s9
	s_add_u32 s8, s8, 0x3000000
	s_add_u32 s98, s88, s8
	s_addc_u32 s99, s89, 0
	global_store_dword v115, v48, s[98:99] nt
	global_store_dword v115, v16, s[98:99] offset:128 nt
	s_add_u32 s98, s98, 0x1000
	s_addc_u32 s99, s99, 0
	global_store_dword v115, v49, s[98:99] nt
	global_store_dword v115, v17, s[98:99] offset:128 nt
	s_add_u32 s98, s98, 0x1000
	s_addc_u32 s99, s99, 0
	global_store_dword v115, v50, s[98:99] nt
	global_store_dword v115, v18, s[98:99] offset:128 nt
	s_add_u32 s98, s98, 0x1000
	s_addc_u32 s99, s99, 0
	global_store_dword v115, v51, s[98:99] nt
	global_store_dword v115, v19, s[98:99] offset:128 nt
	s_add_u32 s98, s98, 0x5000
	s_addc_u32 s99, s99, 0
	global_store_dword v115, v52, s[98:99] nt
	global_store_dword v115, v20, s[98:99] offset:128 nt
	s_add_u32 s98, s98, 0x1000
	s_addc_u32 s99, s99, 0
	global_store_dword v115, v53, s[98:99] nt
	global_store_dword v115, v21, s[98:99] offset:128 nt
	s_add_u32 s98, s98, 0x1000
	s_addc_u32 s99, s99, 0
	global_store_dword v115, v54, s[98:99] nt
	global_store_dword v115, v22, s[98:99] offset:128 nt
	s_add_u32 s98, s98, 0x1000
	s_addc_u32 s99, s99, 0
	global_store_dword v115, v55, s[98:99] nt
	global_store_dword v115, v23, s[98:99] offset:128 nt
	s_add_u32 s98, s98, 0x5000
	s_addc_u32 s99, s99, 0
	global_store_dword v115, v56, s[98:99] nt
	global_store_dword v115, v24, s[98:99] offset:128 nt
	s_add_u32 s98, s98, 0x1000
	s_addc_u32 s99, s99, 0
	global_store_dword v115, v57, s[98:99] nt
	global_store_dword v115, v25, s[98:99] offset:128 nt
	s_add_u32 s98, s98, 0x1000
	s_addc_u32 s99, s99, 0
	global_store_dword v115, v58, s[98:99] nt
	global_store_dword v115, v26, s[98:99] offset:128 nt
	s_add_u32 s98, s98, 0x1000
	s_addc_u32 s99, s99, 0
	global_store_dword v115, v59, s[98:99] nt
	global_store_dword v115, v27, s[98:99] offset:128 nt
	s_add_u32 s98, s98, 0x5000
	s_addc_u32 s99, s99, 0
	global_store_dword v115, v60, s[98:99] nt
	global_store_dword v115, v28, s[98:99] offset:128 nt
	s_add_u32 s98, s98, 0x1000
	s_addc_u32 s99, s99, 0
	global_store_dword v115, v61, s[98:99] nt
	global_store_dword v115, v29, s[98:99] offset:128 nt
	s_add_u32 s98, s98, 0x1000
	s_addc_u32 s99, s99, 0
	global_store_dword v115, v62, s[98:99] nt
	global_store_dword v115, v30, s[98:99] offset:128 nt
	s_add_u32 s98, s98, 0x1000
	s_addc_u32 s99, s99, 0
	global_store_dword v115, v63, s[98:99] nt
	global_store_dword v115, v31, s[98:99] offset:128 nt
	s_add_u32 s98, s98, 0x5000
	s_addc_u32 s99, s99, 0
	global_store_dword v115, v32, s[98:99] nt
	global_store_dword v115, v0, s[98:99] offset:128 nt
	s_add_u32 s98, s98, 0x1000
	s_addc_u32 s99, s99, 0
	global_store_dword v115, v33, s[98:99] nt
	global_store_dword v115, v1, s[98:99] offset:128 nt
	s_add_u32 s98, s98, 0x1000
	s_addc_u32 s99, s99, 0
	global_store_dword v115, v34, s[98:99] nt
	global_store_dword v115, v2, s[98:99] offset:128 nt
	s_add_u32 s98, s98, 0x1000
	s_addc_u32 s99, s99, 0
	global_store_dword v115, v35, s[98:99] nt
	global_store_dword v115, v3, s[98:99] offset:128 nt
	s_add_u32 s98, s98, 0x5000
	s_addc_u32 s99, s99, 0
	global_store_dword v115, v36, s[98:99] nt
	global_store_dword v115, v4, s[98:99] offset:128 nt
	s_add_u32 s98, s98, 0x1000
	s_addc_u32 s99, s99, 0
	global_store_dword v115, v37, s[98:99] nt
	global_store_dword v115, v5, s[98:99] offset:128 nt
	s_add_u32 s98, s98, 0x1000
	s_addc_u32 s99, s99, 0
	global_store_dword v115, v38, s[98:99] nt
	global_store_dword v115, v6, s[98:99] offset:128 nt
	s_add_u32 s98, s98, 0x1000
	s_addc_u32 s99, s99, 0
	global_store_dword v115, v39, s[98:99] nt
	global_store_dword v115, v7, s[98:99] offset:128 nt
	s_add_u32 s98, s98, 0x5000
	s_addc_u32 s99, s99, 0
	global_store_dword v115, v40, s[98:99] nt
	global_store_dword v115, v8, s[98:99] offset:128 nt
	s_add_u32 s98, s98, 0x1000
	s_addc_u32 s99, s99, 0
	global_store_dword v115, v41, s[98:99] nt
	global_store_dword v115, v9, s[98:99] offset:128 nt
	s_add_u32 s98, s98, 0x1000
	s_addc_u32 s99, s99, 0
	global_store_dword v115, v42, s[98:99] nt
	global_store_dword v115, v10, s[98:99] offset:128 nt
	s_add_u32 s98, s98, 0x1000
	s_addc_u32 s99, s99, 0
	global_store_dword v115, v43, s[98:99] nt
	global_store_dword v115, v11, s[98:99] offset:128 nt
	s_add_u32 s98, s98, 0x5000
	s_addc_u32 s99, s99, 0
	global_store_dword v115, v44, s[98:99] nt
	global_store_dword v115, v12, s[98:99] offset:128 nt
	s_add_u32 s98, s98, 0x1000
	s_addc_u32 s99, s99, 0
	global_store_dword v115, v45, s[98:99] nt
	global_store_dword v115, v13, s[98:99] offset:128 nt
	s_add_u32 s98, s98, 0x1000
	s_addc_u32 s99, s99, 0
	global_store_dword v115, v46, s[98:99] nt
	global_store_dword v115, v14, s[98:99] offset:128 nt
	s_add_u32 s98, s98, 0x1000
	s_addc_u32 s99, s99, 0
	global_store_dword v115, v47, s[98:99] nt
	global_store_dword v115, v15, s[98:99] offset:128 nt

.Lodin4_old:
	v_add_u32_e32 v75, s11, v184
	v_bitop3_b32 v74, s10, v155, v186 bitop3:0xc8
	v_or_b32_e32 v130, s10, v186
	v_mul_hi_u32_u24_e32 v67, 0x6000, v74
	v_mul_u32_u24_e32 v66, 0x6000, v74
	s_cmpk_gt_u32 s10, 0x3ff
	v_or_b32_e32 v64, v75, v190
	v_cmp_lt_i32_e64 s[14:15], s49, v130
	s_cselect_b64 s[36:37], -1, 0
	v_cmp_lt_i32_e64 s[12:13], s53, v75
	v_cmp_gt_i32_e64 s[8:9], s54, v75
	v_lshl_add_u64 v[68:69], s[16:17], 0, v[66:67]
	v_ashrrev_i32_e32 v65, 31, v64
	s_and_saveexec_b64 s[6:7], s[14:15]
	s_xor_b64 s[6:7], exec, s[6:7]
	s_cbranch_execz .LBB0_1522
	v_cvt_pk_bf16_f32 v66, v48, v49
	v_cvt_pk_bf16_f32 v67, v50, v51
	v_lshl_add_u64 v[70:71], v[64:65], 1, v[68:69]
	global_store_dwordx2 v[70:71], v[66:67], off
	s_and_saveexec_b64 s[10:11], s[8:9]
	s_cbranch_execz .LBB0_1521
	v_lshlrev_b32_e32 v66, 2, v74
	v_mov_b32_e32 v67, v131
	v_lshl_add_u64 v[66:67], s[28:29], 0, v[66:67]
	v_lshlrev_b64 v[70:71], 12, v[64:65]
	v_lshl_add_u64 v[70:71], v[66:67], 0, v[70:71]
	global_store_dword v[70:71], v48, off nt
	v_or_b32_e32 v70, 1, v64
	v_ashrrev_i32_e32 v71, 31, v70
	v_lshlrev_b64 v[70:71], 12, v[70:71]
	v_lshl_add_u64 v[70:71], v[66:67], 0, v[70:71]
	global_store_dword v[70:71], v49, off nt
	v_or_b32_e32 v70, 2, v64
	v_ashrrev_i32_e32 v71, 31, v70
	v_lshlrev_b64 v[70:71], 12, v[70:71]
	v_lshl_add_u64 v[70:71], v[66:67], 0, v[70:71]
	global_store_dword v[70:71], v50, off nt
	v_or_b32_e32 v70, 3, v64
	v_ashrrev_i32_e32 v71, 31, v70
	v_lshlrev_b64 v[70:71], 12, v[70:71]
	v_lshl_add_u64 v[66:67], v[66:67], 0, v[70:71]
	global_store_dword v[66:67], v51, off nt

.LBB0_1527:
	s_or_b64 exec, exec, s[6:7]
	v_or_b32_e32 v66, 8, v64
	s_and_saveexec_b64 s[6:7], s[14:15]
	s_xor_b64 s[6:7], exec, s[6:7]
	s_cbranch_execz .LBB0_1531
	v_cvt_pk_bf16_f32 v48, v52, v53
	v_cvt_pk_bf16_f32 v49, v54, v55
	v_lshl_add_u64 v[50:51], v[64:65], 1, v[68:69]
	global_store_dwordx2 v[50:51], v[48:49], off offset:16
	s_and_saveexec_b64 s[10:11], s[8:9]
	s_cbranch_execz .LBB0_1530
	v_ashrrev_i32_e32 v67, 31, v66
	v_lshlrev_b32_e32 v48, 2, v74
	v_mov_b32_e32 v49, v131
	v_lshl_add_u64 v[48:49], s[28:29], 0, v[48:49]
	v_lshlrev_b64 v[50:51], 12, v[66:67]
	v_lshl_add_u64 v[50:51], v[48:49], 0, v[50:51]
	global_store_dword v[50:51], v52, off nt
	v_or_b32_e32 v50, 9, v64
	v_ashrrev_i32_e32 v51, 31, v50
	v_lshlrev_b64 v[50:51], 12, v[50:51]
	v_lshl_add_u64 v[50:51], v[48:49], 0, v[50:51]
	global_store_dword v[50:51], v53, off nt
	v_or_b32_e32 v50, 10, v64
	v_ashrrev_i32_e32 v51, 31, v50
	v_lshlrev_b64 v[50:51], 12, v[50:51]
	v_lshl_add_u64 v[50:51], v[48:49], 0, v[50:51]
	global_store_dword v[50:51], v54, off nt
	v_or_b32_e32 v50, 11, v64
	v_ashrrev_i32_e32 v51, 31, v50
	v_lshlrev_b64 v[50:51], 12, v[50:51]
	v_lshl_add_u64 v[48:49], v[48:49], 0, v[50:51]
	global_store_dword v[48:49], v55, off nt

.LBB0_1536:
	s_or_b64 exec, exec, s[6:7]
	v_or_b32_e32 v54, 16, v64
	s_and_saveexec_b64 s[6:7], s[14:15]
	s_xor_b64 s[6:7], exec, s[6:7]
	s_cbranch_execz .LBB0_1540
	v_cvt_pk_bf16_f32 v48, v56, v57
	v_cvt_pk_bf16_f32 v49, v58, v59
	v_lshl_add_u64 v[50:51], v[64:65], 1, v[68:69]
	global_store_dwordx2 v[50:51], v[48:49], off offset:32
	s_and_saveexec_b64 s[10:11], s[8:9]
	s_cbranch_execz .LBB0_1539
	v_ashrrev_i32_e32 v55, 31, v54
	v_lshlrev_b32_e32 v48, 2, v74
	v_mov_b32_e32 v49, v131
	v_lshl_add_u64 v[48:49], s[28:29], 0, v[48:49]
	v_lshlrev_b64 v[50:51], 12, v[54:55]
	v_lshl_add_u64 v[50:51], v[48:49], 0, v[50:51]
	global_store_dword v[50:51], v56, off nt
	v_or_b32_e32 v50, 17, v64
	v_ashrrev_i32_e32 v51, 31, v50
	v_lshlrev_b64 v[50:51], 12, v[50:51]
	v_lshl_add_u64 v[50:51], v[48:49], 0, v[50:51]
	global_store_dword v[50:51], v57, off nt
	v_or_b32_e32 v50, 18, v64
	v_ashrrev_i32_e32 v51, 31, v50
	v_lshlrev_b64 v[50:51], 12, v[50:51]
	v_lshl_add_u64 v[50:51], v[48:49], 0, v[50:51]
	global_store_dword v[50:51], v58, off nt
	v_or_b32_e32 v50, 19, v64
	v_ashrrev_i32_e32 v51, 31, v50
	v_lshlrev_b64 v[50:51], 12, v[50:51]
	v_lshl_add_u64 v[48:49], v[48:49], 0, v[50:51]
	global_store_dword v[48:49], v59, off nt

.LBB0_1545:
	s_or_b64 exec, exec, s[6:7]
	v_or_b32_e32 v52, 24, v64
	s_and_saveexec_b64 s[6:7], s[14:15]
	s_xor_b64 s[6:7], exec, s[6:7]
	s_cbranch_execz .LBB0_1549
	v_cvt_pk_bf16_f32 v48, v60, v61
	v_cvt_pk_bf16_f32 v49, v62, v63
	v_lshl_add_u64 v[50:51], v[64:65], 1, v[68:69]
	global_store_dwordx2 v[50:51], v[48:49], off offset:48
	s_and_saveexec_b64 s[10:11], s[8:9]
	s_cbranch_execz .LBB0_1548
	v_ashrrev_i32_e32 v53, 31, v52
	v_lshlrev_b32_e32 v48, 2, v74
	v_mov_b32_e32 v49, v131
	v_lshl_add_u64 v[48:49], s[28:29], 0, v[48:49]
	v_lshlrev_b64 v[50:51], 12, v[52:53]
	v_lshl_add_u64 v[50:51], v[48:49], 0, v[50:51]
	global_store_dword v[50:51], v60, off nt
	v_or_b32_e32 v50, 25, v64
	v_ashrrev_i32_e32 v51, 31, v50
	v_lshlrev_b64 v[50:51], 12, v[50:51]
	v_lshl_add_u64 v[50:51], v[48:49], 0, v[50:51]
	global_store_dword v[50:51], v61, off nt
	v_or_b32_e32 v50, 26, v64
	v_ashrrev_i32_e32 v51, 31, v50
	v_lshlrev_b64 v[50:51], 12, v[50:51]
	v_lshl_add_u64 v[50:51], v[48:49], 0, v[50:51]
	global_store_dword v[50:51], v62, off nt
	v_or_b32_e32 v50, 27, v64
	v_ashrrev_i32_e32 v51, 31, v50
	v_lshlrev_b64 v[50:51], 12, v[50:51]
	v_lshl_add_u64 v[48:49], v[48:49], 0, v[50:51]
	global_store_dword v[48:49], v63, off nt

.LBB0_1554:
	s_or_b64 exec, exec, s[6:7]
	v_cmp_lt_i32_e64 s[10:11], s56, v75
	v_cmp_gt_i32_e64 s[6:7], s57, v75
	v_or_b32_e32 v50, 32, v64
	s_and_saveexec_b64 s[38:39], s[14:15]
	s_xor_b64 s[38:39], exec, s[38:39]
	s_cbranch_execz .LBB0_1558
	v_cvt_pk_bf16_f32 v48, v32, v33
	v_cvt_pk_bf16_f32 v49, v34, v35
	v_lshl_add_u64 v[56:57], v[64:65], 1, v[68:69]
	global_store_dwordx2 v[56:57], v[48:49], off offset:64
	s_and_saveexec_b64 s[42:43], s[6:7]
	s_cbranch_execz .LBB0_1557
	v_ashrrev_i32_e32 v51, 31, v50
	v_lshlrev_b32_e32 v48, 2, v74
	v_mov_b32_e32 v49, v131
	v_lshl_add_u64 v[48:49], s[28:29], 0, v[48:49]
	v_lshlrev_b64 v[56:57], 12, v[50:51]
	v_lshl_add_u64 v[56:57], v[48:49], 0, v[56:57]
	global_store_dword v[56:57], v32, off nt
	v_or_b32_e32 v56, 33, v64
	v_ashrrev_i32_e32 v57, 31, v56
	v_lshlrev_b64 v[56:57], 12, v[56:57]
	v_lshl_add_u64 v[56:57], v[48:49], 0, v[56:57]
	global_store_dword v[56:57], v33, off nt
	v_or_b32_e32 v56, 34, v64
	v_ashrrev_i32_e32 v57, 31, v56
	v_lshlrev_b64 v[56:57], 12, v[56:57]
	v_lshl_add_u64 v[56:57], v[48:49], 0, v[56:57]
	global_store_dword v[56:57], v34, off nt
	v_or_b32_e32 v56, 35, v64
	v_ashrrev_i32_e32 v57, 31, v56
	v_lshlrev_b64 v[56:57], 12, v[56:57]
	v_lshl_add_u64 v[48:49], v[48:49], 0, v[56:57]
	global_store_dword v[48:49], v35, off nt

.LBB0_1563:
	s_or_b64 exec, exec, s[38:39]
	v_or_b32_e32 v48, 40, v64
	s_and_saveexec_b64 s[38:39], s[14:15]
	s_xor_b64 s[38:39], exec, s[38:39]
	s_cbranch_execz .LBB0_1567
	v_cvt_pk_bf16_f32 v32, v36, v37
	v_cvt_pk_bf16_f32 v33, v38, v39
	v_lshl_add_u64 v[34:35], v[64:65], 1, v[68:69]
	global_store_dwordx2 v[34:35], v[32:33], off offset:80
	s_and_saveexec_b64 s[42:43], s[6:7]
	s_cbranch_execz .LBB0_1566
	v_ashrrev_i32_e32 v49, 31, v48
	v_lshlrev_b32_e32 v32, 2, v74
	v_mov_b32_e32 v33, v131
	v_lshl_add_u64 v[32:33], s[28:29], 0, v[32:33]
	v_lshlrev_b64 v[34:35], 12, v[48:49]
	v_lshl_add_u64 v[34:35], v[32:33], 0, v[34:35]
	global_store_dword v[34:35], v36, off nt
	v_or_b32_e32 v34, 41, v64
	v_ashrrev_i32_e32 v35, 31, v34
	v_lshlrev_b64 v[34:35], 12, v[34:35]
	v_lshl_add_u64 v[34:35], v[32:33], 0, v[34:35]
	global_store_dword v[34:35], v37, off nt
	v_or_b32_e32 v34, 42, v64
	v_ashrrev_i32_e32 v35, 31, v34
	v_lshlrev_b64 v[34:35], 12, v[34:35]
	v_lshl_add_u64 v[34:35], v[32:33], 0, v[34:35]
	global_store_dword v[34:35], v38, off nt
	v_or_b32_e32 v34, 43, v64
	v_ashrrev_i32_e32 v35, 31, v34
	v_lshlrev_b64 v[34:35], 12, v[34:35]
	v_lshl_add_u64 v[32:33], v[32:33], 0, v[34:35]
	global_store_dword v[32:33], v39, off nt

.LBB0_1572:
	s_or_b64 exec, exec, s[38:39]
	v_or_b32_e32 v34, 48, v64
	s_and_saveexec_b64 s[38:39], s[14:15]
	s_xor_b64 s[38:39], exec, s[38:39]
	s_cbranch_execz .LBB0_1576
	v_cvt_pk_bf16_f32 v32, v40, v41
	v_cvt_pk_bf16_f32 v33, v42, v43
	v_lshl_add_u64 v[36:37], v[64:65], 1, v[68:69]
	global_store_dwordx2 v[36:37], v[32:33], off offset:96
	s_and_saveexec_b64 s[42:43], s[6:7]
	s_cbranch_execz .LBB0_1575
	v_ashrrev_i32_e32 v35, 31, v34
	v_lshlrev_b32_e32 v32, 2, v74
	v_mov_b32_e32 v33, v131
	v_lshl_add_u64 v[32:33], s[28:29], 0, v[32:33]
	v_lshlrev_b64 v[36:37], 12, v[34:35]
	v_lshl_add_u64 v[36:37], v[32:33], 0, v[36:37]
	global_store_dword v[36:37], v40, off nt
	v_or_b32_e32 v36, 49, v64
	v_ashrrev_i32_e32 v37, 31, v36
	v_lshlrev_b64 v[36:37], 12, v[36:37]
	v_lshl_add_u64 v[36:37], v[32:33], 0, v[36:37]
	global_store_dword v[36:37], v41, off nt
	v_or_b32_e32 v36, 50, v64
	v_ashrrev_i32_e32 v37, 31, v36
	v_lshlrev_b64 v[36:37], 12, v[36:37]
	v_lshl_add_u64 v[36:37], v[32:33], 0, v[36:37]
	global_store_dword v[36:37], v42, off nt
	v_or_b32_e32 v36, 51, v64
	v_ashrrev_i32_e32 v37, 31, v36
	v_lshlrev_b64 v[36:37], 12, v[36:37]
	v_lshl_add_u64 v[32:33], v[32:33], 0, v[36:37]
	global_store_dword v[32:33], v43, off nt

.LBB0_1581:
	s_or_b64 exec, exec, s[38:39]
	v_or_b32_e32 v32, 56, v64
	s_and_saveexec_b64 s[38:39], s[14:15]
	s_xor_b64 s[14:15], exec, s[38:39]
	s_cbranch_execz .LBB0_1585
	v_cvt_pk_bf16_f32 v36, v44, v45
	v_cvt_pk_bf16_f32 v37, v46, v47
	v_lshl_add_u64 v[38:39], v[64:65], 1, v[68:69]
	global_store_dwordx2 v[38:39], v[36:37], off offset:112
	s_and_saveexec_b64 s[38:39], s[6:7]
	s_cbranch_execz .LBB0_1584
	v_ashrrev_i32_e32 v33, 31, v32
	v_lshlrev_b32_e32 v36, 2, v74
	v_mov_b32_e32 v37, v131
	v_lshl_add_u64 v[36:37], s[28:29], 0, v[36:37]
	v_lshlrev_b64 v[38:39], 12, v[32:33]
	v_lshl_add_u64 v[38:39], v[36:37], 0, v[38:39]
	global_store_dword v[38:39], v44, off nt
	v_or_b32_e32 v38, 57, v64
	v_ashrrev_i32_e32 v39, 31, v38
	v_lshlrev_b64 v[38:39], 12, v[38:39]
	v_lshl_add_u64 v[38:39], v[36:37], 0, v[38:39]
	global_store_dword v[38:39], v45, off nt
	v_or_b32_e32 v38, 58, v64
	v_ashrrev_i32_e32 v39, 31, v38
	v_lshlrev_b64 v[38:39], 12, v[38:39]
	v_lshl_add_u64 v[38:39], v[36:37], 0, v[38:39]
	global_store_dword v[38:39], v46, off nt
	v_or_b32_e32 v38, 59, v64
	v_ashrrev_i32_e32 v39, 31, v38
	v_lshlrev_b64 v[38:39], 12, v[38:39]
	v_lshl_add_u64 v[36:37], v[36:37], 0, v[38:39]
	global_store_dword v[36:37], v47, off nt

.LBB0_1590:
	s_or_b64 exec, exec, s[14:15]
	v_bitop3_b32 v44, v130, s52, 32 bitop3:0xc8
	v_mul_hi_u32_u24_e32 v37, 0x6000, v44
	v_mul_u32_u24_e32 v36, 0x6000, v44
	v_cmp_lt_i32_e64 s[14:15], s58, v130
	v_lshl_add_u64 v[36:37], s[16:17], 0, v[36:37]
	s_and_saveexec_b64 s[38:39], s[14:15]
	s_xor_b64 s[38:39], exec, s[38:39]
	s_cbranch_execz .LBB0_1594
	v_cvt_pk_bf16_f32 v38, v16, v17
	v_cvt_pk_bf16_f32 v39, v18, v19
	v_lshl_add_u64 v[40:41], v[64:65], 1, v[36:37]
	global_store_dwordx2 v[40:41], v[38:39], off
	s_and_saveexec_b64 s[42:43], s[8:9]
	s_cbranch_execz .LBB0_1593
	v_lshlrev_b32_e32 v38, 2, v44
	v_mov_b32_e32 v39, v131
	v_lshl_add_u64 v[38:39], s[28:29], 0, v[38:39]
	v_lshlrev_b64 v[40:41], 12, v[64:65]
	v_lshl_add_u64 v[40:41], v[38:39], 0, v[40:41]
	global_store_dword v[40:41], v16, off nt
	v_or_b32_e32 v40, 1, v64
	v_ashrrev_i32_e32 v41, 31, v40
	v_lshlrev_b64 v[40:41], 12, v[40:41]
	v_lshl_add_u64 v[40:41], v[38:39], 0, v[40:41]
	global_store_dword v[40:41], v17, off nt
	v_or_b32_e32 v40, 2, v64
	v_ashrrev_i32_e32 v41, 31, v40
	v_lshlrev_b64 v[40:41], 12, v[40:41]
	v_lshl_add_u64 v[40:41], v[38:39], 0, v[40:41]
	global_store_dword v[40:41], v18, off nt
	v_or_b32_e32 v40, 3, v64
	v_ashrrev_i32_e32 v41, 31, v40
	v_lshlrev_b64 v[40:41], 12, v[40:41]
	v_lshl_add_u64 v[38:39], v[38:39], 0, v[40:41]
	global_store_dword v[38:39], v19, off nt

.LBB0_1597:
	s_or_b64 exec, exec, s[42:43]
	v_or_b32_e32 v42, 1, v64
	v_or_b32_e32 v40, 2, v64
	v_or_b32_e32 v38, 3, v64
	s_mov_b64 s[42:43], -1
	s_andn2_b64 vcc, exec, s[36:37]
	v_ashrrev_i32_e32 v43, 31, v42
	v_ashrrev_i32_e32 v41, 31, v40
	v_ashrrev_i32_e32 v39, 31, v38
	s_cbranch_vccnz .LBB0_1601
	v_lshlrev_b32_e32 v46, 1, v44
	v_mov_b32_e32 v47, v131
	v_lshl_add_u64 v[46:47], s[0:1], 0, v[46:47]
	v_lshlrev_b64 v[56:57], 11, v[64:65]
	v_cvt_pk_bf16_f32 v33, v16, s0
	v_lshl_add_u64 v[56:57], v[46:47], 0, v[56:57]
	global_store_short v[56:57], v33, off
	v_lshlrev_b64 v[56:57], 11, v[42:43]
	v_cvt_pk_bf16_f32 v33, v17, s0
	v_lshl_add_u64 v[56:57], v[46:47], 0, v[56:57]
	global_store_short v[56:57], v33, off
	v_lshlrev_b64 v[56:57], 11, v[40:41]
	v_cvt_pk_bf16_f32 v33, v18, s0
	v_lshl_add_u64 v[56:57], v[46:47], 0, v[56:57]
	global_store_short v[56:57], v33, off
	v_lshlrev_b64 v[56:57], 11, v[38:39]
	v_cvt_pk_bf16_f32 v33, v19, s0
	v_lshl_add_u64 v[46:47], v[46:47], 0, v[56:57]
	global_store_short v[46:47], v33, off
	s_and_saveexec_b64 s[42:43], s[8:9]
	s_cbranch_execz .LBB0_1600
	v_lshlrev_b32_e32 v46, 2, v44
	v_mov_b32_e32 v47, v131
	v_lshl_add_u64 v[46:47], s[96:97], 0, v[46:47]
	v_lshlrev_b64 v[56:57], 12, v[64:65]
	v_lshl_add_u64 v[56:57], v[46:47], 0, v[56:57]
	global_store_dword v[56:57], v16, off nt
	v_lshlrev_b64 v[56:57], 12, v[42:43]
	v_lshl_add_u64 v[56:57], v[46:47], 0, v[56:57]
	global_store_dword v[56:57], v17, off nt
	v_lshlrev_b64 v[56:57], 12, v[40:41]
	v_lshl_add_u64 v[56:57], v[46:47], 0, v[56:57]
	global_store_dword v[56:57], v18, off nt
	v_lshlrev_b64 v[56:57], 12, v[38:39]
	v_lshl_add_u64 v[46:47], v[46:47], 0, v[56:57]
	global_store_dword v[46:47], v19, off nt

.LBB0_1603:
	s_or_b64 exec, exec, s[38:39]
	s_and_saveexec_b64 s[38:39], s[14:15]
	s_xor_b64 s[38:39], exec, s[38:39]
	s_cbranch_execz .LBB0_1607
	v_cvt_pk_bf16_f32 v16, v20, v21
	v_cvt_pk_bf16_f32 v17, v22, v23
	v_lshl_add_u64 v[18:19], v[64:65], 1, v[36:37]
	global_store_dwordx2 v[18:19], v[16:17], off offset:16
	s_and_saveexec_b64 s[42:43], s[8:9]
	s_cbranch_execz .LBB0_1606
	v_ashrrev_i32_e32 v67, 31, v66
	v_lshlrev_b32_e32 v16, 2, v44
	v_mov_b32_e32 v17, v131
	v_lshl_add_u64 v[16:17], s[28:29], 0, v[16:17]
	v_lshlrev_b64 v[18:19], 12, v[66:67]
	v_lshl_add_u64 v[18:19], v[16:17], 0, v[18:19]
	global_store_dword v[18:19], v20, off nt
	v_or_b32_e32 v18, 9, v64
	v_ashrrev_i32_e32 v19, 31, v18
	v_lshlrev_b64 v[18:19], 12, v[18:19]
	v_lshl_add_u64 v[18:19], v[16:17], 0, v[18:19]
	global_store_dword v[18:19], v21, off nt
	v_or_b32_e32 v18, 10, v64
	v_ashrrev_i32_e32 v19, 31, v18
	v_lshlrev_b64 v[18:19], 12, v[18:19]
	v_lshl_add_u64 v[18:19], v[16:17], 0, v[18:19]
	global_store_dword v[18:19], v22, off nt
	v_or_b32_e32 v18, 11, v64
	v_ashrrev_i32_e32 v19, 31, v18
	v_lshlrev_b64 v[18:19], 12, v[18:19]
	v_lshl_add_u64 v[16:17], v[16:17], 0, v[18:19]
	global_store_dword v[16:17], v23, off nt

.LBB0_1610:
	s_or_b64 exec, exec, s[42:43]
	v_or_b32_e32 v38, 9, v64
	v_or_b32_e32 v18, 10, v64
	v_or_b32_e32 v16, 11, v64
	s_mov_b64 s[42:43], -1
	s_andn2_b64 vcc, exec, s[36:37]
	v_ashrrev_i32_e32 v67, 31, v66
	v_ashrrev_i32_e32 v39, 31, v38
	v_ashrrev_i32_e32 v19, 31, v18
	v_ashrrev_i32_e32 v17, 31, v16
	s_cbranch_vccnz .LBB0_1614
	v_lshlrev_b32_e32 v40, 1, v44
	v_mov_b32_e32 v41, v131
	v_lshl_add_u64 v[40:41], s[0:1], 0, v[40:41]
	v_lshlrev_b64 v[42:43], 11, v[66:67]
	v_cvt_pk_bf16_f32 v33, v20, s0
	v_lshl_add_u64 v[42:43], v[40:41], 0, v[42:43]
	global_store_short v[42:43], v33, off
	v_lshlrev_b64 v[42:43], 11, v[38:39]
	v_cvt_pk_bf16_f32 v33, v21, s0
	v_lshl_add_u64 v[42:43], v[40:41], 0, v[42:43]
	global_store_short v[42:43], v33, off
	v_lshlrev_b64 v[42:43], 11, v[18:19]
	v_cvt_pk_bf16_f32 v33, v22, s0
	v_lshl_add_u64 v[42:43], v[40:41], 0, v[42:43]
	global_store_short v[42:43], v33, off
	v_lshlrev_b64 v[42:43], 11, v[16:17]
	v_cvt_pk_bf16_f32 v33, v23, s0
	v_lshl_add_u64 v[40:41], v[40:41], 0, v[42:43]
	global_store_short v[40:41], v33, off
	s_and_saveexec_b64 s[42:43], s[8:9]
	s_cbranch_execz .LBB0_1613
	v_lshlrev_b32_e32 v40, 2, v44
	v_mov_b32_e32 v41, v131
	v_lshl_add_u64 v[40:41], s[96:97], 0, v[40:41]
	v_lshlrev_b64 v[42:43], 12, v[66:67]
	v_lshl_add_u64 v[42:43], v[40:41], 0, v[42:43]
	global_store_dword v[42:43], v20, off nt
	v_lshlrev_b64 v[42:43], 12, v[38:39]
	v_lshl_add_u64 v[42:43], v[40:41], 0, v[42:43]
	global_store_dword v[42:43], v21, off nt
	v_lshlrev_b64 v[42:43], 12, v[18:19]
	v_lshl_add_u64 v[42:43], v[40:41], 0, v[42:43]
	global_store_dword v[42:43], v22, off nt
	v_lshlrev_b64 v[42:43], 12, v[16:17]
	v_lshl_add_u64 v[40:41], v[40:41], 0, v[42:43]
	global_store_dword v[40:41], v23, off nt

.LBB0_1616:
	s_or_b64 exec, exec, s[38:39]
	s_and_saveexec_b64 s[38:39], s[14:15]
	s_xor_b64 s[38:39], exec, s[38:39]
	s_cbranch_execz .LBB0_1620
	v_cvt_pk_bf16_f32 v16, v24, v25
	v_cvt_pk_bf16_f32 v17, v26, v27
	v_lshl_add_u64 v[18:19], v[64:65], 1, v[36:37]
	global_store_dwordx2 v[18:19], v[16:17], off offset:32
	s_and_saveexec_b64 s[42:43], s[8:9]
	s_cbranch_execz .LBB0_1619
	v_ashrrev_i32_e32 v55, 31, v54
	v_lshlrev_b32_e32 v16, 2, v44
	v_mov_b32_e32 v17, v131
	v_lshl_add_u64 v[16:17], s[28:29], 0, v[16:17]
	v_lshlrev_b64 v[18:19], 12, v[54:55]
	v_lshl_add_u64 v[18:19], v[16:17], 0, v[18:19]
	global_store_dword v[18:19], v24, off nt
	v_or_b32_e32 v18, 17, v64
	v_ashrrev_i32_e32 v19, 31, v18
	v_lshlrev_b64 v[18:19], 12, v[18:19]
	v_lshl_add_u64 v[18:19], v[16:17], 0, v[18:19]
	global_store_dword v[18:19], v25, off nt
	v_or_b32_e32 v18, 18, v64
	v_ashrrev_i32_e32 v19, 31, v18
	v_lshlrev_b64 v[18:19], 12, v[18:19]
	v_lshl_add_u64 v[18:19], v[16:17], 0, v[18:19]
	global_store_dword v[18:19], v26, off nt
	v_or_b32_e32 v18, 19, v64
	v_ashrrev_i32_e32 v19, 31, v18
	v_lshlrev_b64 v[18:19], 12, v[18:19]
	v_lshl_add_u64 v[16:17], v[16:17], 0, v[18:19]
	global_store_dword v[16:17], v27, off nt

.LBB0_1623:
	s_or_b64 exec, exec, s[42:43]
	v_or_b32_e32 v20, 17, v64
	v_or_b32_e32 v18, 18, v64
	v_or_b32_e32 v16, 19, v64
	s_mov_b64 s[42:43], -1
	s_andn2_b64 vcc, exec, s[36:37]
	v_ashrrev_i32_e32 v55, 31, v54
	v_ashrrev_i32_e32 v21, 31, v20
	v_ashrrev_i32_e32 v19, 31, v18
	v_ashrrev_i32_e32 v17, 31, v16
	s_cbranch_vccnz .LBB0_1627
	v_lshlrev_b32_e32 v22, 1, v44
	v_mov_b32_e32 v23, v131
	v_lshl_add_u64 v[22:23], s[0:1], 0, v[22:23]
	v_lshlrev_b64 v[38:39], 11, v[54:55]
	v_cvt_pk_bf16_f32 v33, v24, s0
	v_lshl_add_u64 v[38:39], v[22:23], 0, v[38:39]
	global_store_short v[38:39], v33, off
	v_lshlrev_b64 v[38:39], 11, v[20:21]
	v_cvt_pk_bf16_f32 v33, v25, s0
	v_lshl_add_u64 v[38:39], v[22:23], 0, v[38:39]
	global_store_short v[38:39], v33, off
	v_lshlrev_b64 v[38:39], 11, v[18:19]
	v_cvt_pk_bf16_f32 v33, v26, s0
	v_lshl_add_u64 v[38:39], v[22:23], 0, v[38:39]
	global_store_short v[38:39], v33, off
	v_lshlrev_b64 v[38:39], 11, v[16:17]
	v_cvt_pk_bf16_f32 v33, v27, s0
	v_lshl_add_u64 v[22:23], v[22:23], 0, v[38:39]
	global_store_short v[22:23], v33, off
	s_and_saveexec_b64 s[42:43], s[8:9]
	s_cbranch_execz .LBB0_1626
	v_lshlrev_b32_e32 v22, 2, v44
	v_mov_b32_e32 v23, v131
	v_lshl_add_u64 v[22:23], s[96:97], 0, v[22:23]
	v_lshlrev_b64 v[38:39], 12, v[54:55]
	v_lshl_add_u64 v[38:39], v[22:23], 0, v[38:39]
	global_store_dword v[38:39], v24, off nt
	v_lshlrev_b64 v[38:39], 12, v[20:21]
	v_lshl_add_u64 v[38:39], v[22:23], 0, v[38:39]
	global_store_dword v[38:39], v25, off nt
	v_lshlrev_b64 v[38:39], 12, v[18:19]
	v_lshl_add_u64 v[38:39], v[22:23], 0, v[38:39]
	global_store_dword v[38:39], v26, off nt
	v_lshlrev_b64 v[38:39], 12, v[16:17]
	v_lshl_add_u64 v[22:23], v[22:23], 0, v[38:39]
	global_store_dword v[22:23], v27, off nt

.LBB0_1629:
	s_or_b64 exec, exec, s[38:39]
	s_and_saveexec_b64 s[38:39], s[14:15]
	s_xor_b64 s[38:39], exec, s[38:39]
	s_cbranch_execz .LBB0_1633
	v_cvt_pk_bf16_f32 v16, v28, v29
	v_cvt_pk_bf16_f32 v17, v30, v31
	v_lshl_add_u64 v[18:19], v[64:65], 1, v[36:37]
	global_store_dwordx2 v[18:19], v[16:17], off offset:48
	s_and_saveexec_b64 s[42:43], s[8:9]
	s_cbranch_execz .LBB0_1632
	v_ashrrev_i32_e32 v53, 31, v52
	v_lshlrev_b32_e32 v16, 2, v44
	v_mov_b32_e32 v17, v131
	v_lshl_add_u64 v[16:17], s[28:29], 0, v[16:17]
	v_lshlrev_b64 v[18:19], 12, v[52:53]
	v_lshl_add_u64 v[18:19], v[16:17], 0, v[18:19]
	global_store_dword v[18:19], v28, off nt
	v_or_b32_e32 v18, 25, v64
	v_ashrrev_i32_e32 v19, 31, v18
	v_lshlrev_b64 v[18:19], 12, v[18:19]
	v_lshl_add_u64 v[18:19], v[16:17], 0, v[18:19]
	global_store_dword v[18:19], v29, off nt
	v_or_b32_e32 v18, 26, v64
	v_ashrrev_i32_e32 v19, 31, v18
	v_lshlrev_b64 v[18:19], 12, v[18:19]
	v_lshl_add_u64 v[18:19], v[16:17], 0, v[18:19]
	global_store_dword v[18:19], v30, off nt
	v_or_b32_e32 v18, 27, v64
	v_ashrrev_i32_e32 v19, 31, v18
	v_lshlrev_b64 v[18:19], 12, v[18:19]
	v_lshl_add_u64 v[16:17], v[16:17], 0, v[18:19]
	global_store_dword v[16:17], v31, off nt

.LBB0_1636:
	s_or_b64 exec, exec, s[42:43]
	v_or_b32_e32 v20, 25, v64
	v_or_b32_e32 v18, 26, v64
	v_or_b32_e32 v16, 27, v64
	s_mov_b64 s[12:13], -1
	s_andn2_b64 vcc, exec, s[36:37]
	v_ashrrev_i32_e32 v53, 31, v52
	v_ashrrev_i32_e32 v21, 31, v20
	v_ashrrev_i32_e32 v19, 31, v18
	v_ashrrev_i32_e32 v17, 31, v16
	s_cbranch_vccnz .LBB0_1640
	v_lshlrev_b32_e32 v22, 1, v44
	v_mov_b32_e32 v23, v131
	v_lshl_add_u64 v[22:23], s[0:1], 0, v[22:23]
	v_lshlrev_b64 v[24:25], 11, v[52:53]
	v_cvt_pk_bf16_f32 v26, v28, s0
	v_lshl_add_u64 v[24:25], v[22:23], 0, v[24:25]
	global_store_short v[24:25], v26, off
	v_lshlrev_b64 v[24:25], 11, v[20:21]
	v_cvt_pk_bf16_f32 v26, v29, s0
	v_lshl_add_u64 v[24:25], v[22:23], 0, v[24:25]
	global_store_short v[24:25], v26, off
	v_lshlrev_b64 v[24:25], 11, v[18:19]
	v_cvt_pk_bf16_f32 v26, v30, s0
	v_lshl_add_u64 v[24:25], v[22:23], 0, v[24:25]
	global_store_short v[24:25], v26, off
	v_lshlrev_b64 v[24:25], 11, v[16:17]
	v_cvt_pk_bf16_f32 v26, v31, s0
	v_lshl_add_u64 v[22:23], v[22:23], 0, v[24:25]
	global_store_short v[22:23], v26, off
	s_and_saveexec_b64 s[12:13], s[8:9]
	s_cbranch_execz .LBB0_1639
	v_lshlrev_b32_e32 v22, 2, v44
	v_mov_b32_e32 v23, v131
	v_lshl_add_u64 v[22:23], s[96:97], 0, v[22:23]
	v_lshlrev_b64 v[24:25], 12, v[52:53]
	v_lshl_add_u64 v[24:25], v[22:23], 0, v[24:25]
	global_store_dword v[24:25], v28, off nt
	v_lshlrev_b64 v[24:25], 12, v[20:21]
	v_lshl_add_u64 v[24:25], v[22:23], 0, v[24:25]
	global_store_dword v[24:25], v29, off nt
	v_lshlrev_b64 v[24:25], 12, v[18:19]
	v_lshl_add_u64 v[24:25], v[22:23], 0, v[24:25]
	global_store_dword v[24:25], v30, off nt
	v_lshlrev_b64 v[24:25], 12, v[16:17]
	v_lshl_add_u64 v[22:23], v[22:23], 0, v[24:25]
	global_store_dword v[22:23], v31, off nt

.LBB0_1642:
	s_or_b64 exec, exec, s[38:39]
	s_and_saveexec_b64 s[8:9], s[14:15]
	s_xor_b64 s[8:9], exec, s[8:9]
	s_cbranch_execz .LBB0_1646
	v_cvt_pk_bf16_f32 v16, v0, v1
	v_cvt_pk_bf16_f32 v17, v2, v3
	v_lshl_add_u64 v[18:19], v[64:65], 1, v[36:37]
	global_store_dwordx2 v[18:19], v[16:17], off offset:64
	s_and_saveexec_b64 s[12:13], s[6:7]
	s_cbranch_execz .LBB0_1645
	v_ashrrev_i32_e32 v51, 31, v50
	v_lshlrev_b32_e32 v16, 2, v44
	v_mov_b32_e32 v17, v131
	v_lshl_add_u64 v[16:17], s[28:29], 0, v[16:17]
	v_lshlrev_b64 v[18:19], 12, v[50:51]
	v_lshl_add_u64 v[18:19], v[16:17], 0, v[18:19]
	global_store_dword v[18:19], v0, off nt
	v_or_b32_e32 v18, 33, v64
	v_ashrrev_i32_e32 v19, 31, v18
	v_lshlrev_b64 v[18:19], 12, v[18:19]
	v_lshl_add_u64 v[18:19], v[16:17], 0, v[18:19]
	global_store_dword v[18:19], v1, off nt
	v_or_b32_e32 v18, 34, v64
	v_ashrrev_i32_e32 v19, 31, v18
	v_lshlrev_b64 v[18:19], 12, v[18:19]
	v_lshl_add_u64 v[18:19], v[16:17], 0, v[18:19]
	global_store_dword v[18:19], v2, off nt
	v_or_b32_e32 v18, 35, v64
	v_ashrrev_i32_e32 v19, 31, v18
	v_lshlrev_b64 v[18:19], 12, v[18:19]
	v_lshl_add_u64 v[16:17], v[16:17], 0, v[18:19]
	global_store_dword v[16:17], v3, off nt

.LBB0_1649:
	s_or_b64 exec, exec, s[12:13]
	v_or_b32_e32 v20, 33, v64
	v_or_b32_e32 v18, 34, v64
	v_or_b32_e32 v16, 35, v64
	s_mov_b64 s[12:13], -1
	s_andn2_b64 vcc, exec, s[36:37]
	v_ashrrev_i32_e32 v51, 31, v50
	v_ashrrev_i32_e32 v21, 31, v20
	v_ashrrev_i32_e32 v19, 31, v18
	v_ashrrev_i32_e32 v17, 31, v16
	s_cbranch_vccnz .LBB0_1653
	v_lshlrev_b32_e32 v22, 1, v44
	v_mov_b32_e32 v23, v131
	v_lshl_add_u64 v[22:23], s[0:1], 0, v[22:23]
	v_lshlrev_b64 v[24:25], 11, v[50:51]
	v_cvt_pk_bf16_f32 v26, v0, s0
	v_lshl_add_u64 v[24:25], v[22:23], 0, v[24:25]
	global_store_short v[24:25], v26, off
	v_lshlrev_b64 v[24:25], 11, v[20:21]
	v_cvt_pk_bf16_f32 v26, v1, s0
	v_lshl_add_u64 v[24:25], v[22:23], 0, v[24:25]
	global_store_short v[24:25], v26, off
	v_lshlrev_b64 v[24:25], 11, v[18:19]
	v_cvt_pk_bf16_f32 v26, v2, s0
	v_lshl_add_u64 v[24:25], v[22:23], 0, v[24:25]
	global_store_short v[24:25], v26, off
	v_lshlrev_b64 v[24:25], 11, v[16:17]
	v_cvt_pk_bf16_f32 v26, v3, s0
	v_lshl_add_u64 v[22:23], v[22:23], 0, v[24:25]
	global_store_short v[22:23], v26, off
	s_and_saveexec_b64 s[12:13], s[6:7]
	s_cbranch_execz .LBB0_1652
	v_lshlrev_b32_e32 v22, 2, v44
	v_mov_b32_e32 v23, v131
	v_lshl_add_u64 v[22:23], s[96:97], 0, v[22:23]
	v_lshlrev_b64 v[24:25], 12, v[50:51]
	v_lshl_add_u64 v[24:25], v[22:23], 0, v[24:25]
	global_store_dword v[24:25], v0, off nt
	v_lshlrev_b64 v[24:25], 12, v[20:21]
	v_lshl_add_u64 v[24:25], v[22:23], 0, v[24:25]
	global_store_dword v[24:25], v1, off nt
	v_lshlrev_b64 v[24:25], 12, v[18:19]
	v_lshl_add_u64 v[24:25], v[22:23], 0, v[24:25]
	global_store_dword v[24:25], v2, off nt
	v_lshlrev_b64 v[24:25], 12, v[16:17]
	v_lshl_add_u64 v[22:23], v[22:23], 0, v[24:25]
	global_store_dword v[22:23], v3, off nt

.LBB0_1655:
	s_or_b64 exec, exec, s[8:9]
	s_and_saveexec_b64 s[8:9], s[14:15]
	s_xor_b64 s[8:9], exec, s[8:9]
	s_cbranch_execz .LBB0_1659
	v_cvt_pk_bf16_f32 v0, v4, v5
	v_cvt_pk_bf16_f32 v1, v6, v7
	v_lshl_add_u64 v[2:3], v[64:65], 1, v[36:37]
	global_store_dwordx2 v[2:3], v[0:1], off offset:80
	s_and_saveexec_b64 s[12:13], s[6:7]
	s_cbranch_execz .LBB0_1658
	v_ashrrev_i32_e32 v49, 31, v48
	v_lshlrev_b32_e32 v0, 2, v44
	v_mov_b32_e32 v1, v131
	v_lshl_add_u64 v[0:1], s[28:29], 0, v[0:1]
	v_lshlrev_b64 v[2:3], 12, v[48:49]
	v_lshl_add_u64 v[2:3], v[0:1], 0, v[2:3]
	global_store_dword v[2:3], v4, off nt
	v_or_b32_e32 v2, 41, v64
	v_ashrrev_i32_e32 v3, 31, v2
	v_lshlrev_b64 v[2:3], 12, v[2:3]
	v_lshl_add_u64 v[2:3], v[0:1], 0, v[2:3]
	global_store_dword v[2:3], v5, off nt
	v_or_b32_e32 v2, 42, v64
	v_ashrrev_i32_e32 v3, 31, v2
	v_lshlrev_b64 v[2:3], 12, v[2:3]
	v_lshl_add_u64 v[2:3], v[0:1], 0, v[2:3]
	global_store_dword v[2:3], v6, off nt
	v_or_b32_e32 v2, 43, v64
	v_ashrrev_i32_e32 v3, 31, v2
	v_lshlrev_b64 v[2:3], 12, v[2:3]
	v_lshl_add_u64 v[0:1], v[0:1], 0, v[2:3]
	global_store_dword v[0:1], v7, off nt

.LBB0_1662:
	s_or_b64 exec, exec, s[12:13]
	v_or_b32_e32 v16, 41, v64
	v_or_b32_e32 v2, 42, v64
	v_or_b32_e32 v0, 43, v64
	s_mov_b64 s[12:13], -1
	s_andn2_b64 vcc, exec, s[36:37]
	v_ashrrev_i32_e32 v49, 31, v48
	v_ashrrev_i32_e32 v17, 31, v16
	v_ashrrev_i32_e32 v3, 31, v2
	v_ashrrev_i32_e32 v1, 31, v0
	s_cbranch_vccnz .LBB0_1666
	v_lshlrev_b32_e32 v18, 1, v44
	v_mov_b32_e32 v19, v131
	v_lshl_add_u64 v[18:19], s[0:1], 0, v[18:19]
	v_lshlrev_b64 v[20:21], 11, v[48:49]
	v_cvt_pk_bf16_f32 v22, v4, s0
	v_lshl_add_u64 v[20:21], v[18:19], 0, v[20:21]
	global_store_short v[20:21], v22, off
	v_lshlrev_b64 v[20:21], 11, v[16:17]
	v_cvt_pk_bf16_f32 v22, v5, s0
	v_lshl_add_u64 v[20:21], v[18:19], 0, v[20:21]
	global_store_short v[20:21], v22, off
	v_lshlrev_b64 v[20:21], 11, v[2:3]
	v_cvt_pk_bf16_f32 v22, v6, s0
	v_lshl_add_u64 v[20:21], v[18:19], 0, v[20:21]
	global_store_short v[20:21], v22, off
	v_lshlrev_b64 v[20:21], 11, v[0:1]
	v_cvt_pk_bf16_f32 v22, v7, s0
	v_lshl_add_u64 v[18:19], v[18:19], 0, v[20:21]
	global_store_short v[18:19], v22, off
	s_and_saveexec_b64 s[12:13], s[6:7]
	s_cbranch_execz .LBB0_1665
	v_lshlrev_b32_e32 v18, 2, v44
	v_mov_b32_e32 v19, v131
	v_lshl_add_u64 v[18:19], s[96:97], 0, v[18:19]
	v_lshlrev_b64 v[20:21], 12, v[48:49]
	v_lshl_add_u64 v[20:21], v[18:19], 0, v[20:21]
	global_store_dword v[20:21], v4, off nt
	v_lshlrev_b64 v[20:21], 12, v[16:17]
	v_lshl_add_u64 v[20:21], v[18:19], 0, v[20:21]
	global_store_dword v[20:21], v5, off nt
	v_lshlrev_b64 v[20:21], 12, v[2:3]
	v_lshl_add_u64 v[20:21], v[18:19], 0, v[20:21]
	global_store_dword v[20:21], v6, off nt
	v_lshlrev_b64 v[20:21], 12, v[0:1]
	v_lshl_add_u64 v[18:19], v[18:19], 0, v[20:21]
	global_store_dword v[18:19], v7, off nt

.LBB0_1668:
	s_or_b64 exec, exec, s[8:9]
	s_and_saveexec_b64 s[8:9], s[14:15]
	s_xor_b64 s[8:9], exec, s[8:9]
	s_cbranch_execz .LBB0_1672
	v_cvt_pk_bf16_f32 v0, v8, v9
	v_cvt_pk_bf16_f32 v1, v10, v11
	v_lshl_add_u64 v[2:3], v[64:65], 1, v[36:37]
	global_store_dwordx2 v[2:3], v[0:1], off offset:96
	s_and_saveexec_b64 s[12:13], s[6:7]
	s_cbranch_execz .LBB0_1671
	v_ashrrev_i32_e32 v35, 31, v34
	v_lshlrev_b32_e32 v0, 2, v44
	v_mov_b32_e32 v1, v131
	v_lshl_add_u64 v[0:1], s[28:29], 0, v[0:1]
	v_lshlrev_b64 v[2:3], 12, v[34:35]
	v_lshl_add_u64 v[2:3], v[0:1], 0, v[2:3]
	global_store_dword v[2:3], v8, off nt
	v_or_b32_e32 v2, 49, v64
	v_ashrrev_i32_e32 v3, 31, v2
	v_lshlrev_b64 v[2:3], 12, v[2:3]
	v_lshl_add_u64 v[2:3], v[0:1], 0, v[2:3]
	global_store_dword v[2:3], v9, off nt
	v_or_b32_e32 v2, 50, v64
	v_ashrrev_i32_e32 v3, 31, v2
	v_lshlrev_b64 v[2:3], 12, v[2:3]
	v_lshl_add_u64 v[2:3], v[0:1], 0, v[2:3]
	global_store_dword v[2:3], v10, off nt
	v_or_b32_e32 v2, 51, v64
	v_ashrrev_i32_e32 v3, 31, v2
	v_lshlrev_b64 v[2:3], 12, v[2:3]
	v_lshl_add_u64 v[0:1], v[0:1], 0, v[2:3]
	global_store_dword v[0:1], v11, off nt

.LBB0_1675:
	s_or_b64 exec, exec, s[12:13]
	v_or_b32_e32 v4, 49, v64
	v_or_b32_e32 v2, 50, v64
	v_or_b32_e32 v0, 51, v64
	s_mov_b64 s[12:13], -1
	s_andn2_b64 vcc, exec, s[36:37]
	v_ashrrev_i32_e32 v35, 31, v34
	v_ashrrev_i32_e32 v5, 31, v4
	v_ashrrev_i32_e32 v3, 31, v2
	v_ashrrev_i32_e32 v1, 31, v0
	s_cbranch_vccnz .LBB0_1679
	v_lshlrev_b32_e32 v6, 1, v44
	v_mov_b32_e32 v7, v131
	v_lshl_add_u64 v[6:7], s[0:1], 0, v[6:7]
	v_lshlrev_b64 v[16:17], 11, v[34:35]
	v_cvt_pk_bf16_f32 v18, v8, s0
	v_lshl_add_u64 v[16:17], v[6:7], 0, v[16:17]
	global_store_short v[16:17], v18, off
	v_lshlrev_b64 v[16:17], 11, v[4:5]
	v_cvt_pk_bf16_f32 v18, v9, s0
	v_lshl_add_u64 v[16:17], v[6:7], 0, v[16:17]
	global_store_short v[16:17], v18, off
	v_lshlrev_b64 v[16:17], 11, v[2:3]
	v_cvt_pk_bf16_f32 v18, v10, s0
	v_lshl_add_u64 v[16:17], v[6:7], 0, v[16:17]
	global_store_short v[16:17], v18, off
	v_lshlrev_b64 v[16:17], 11, v[0:1]
	v_cvt_pk_bf16_f32 v18, v11, s0
	v_lshl_add_u64 v[6:7], v[6:7], 0, v[16:17]
	global_store_short v[6:7], v18, off
	s_and_saveexec_b64 s[12:13], s[6:7]
	s_cbranch_execz .LBB0_1678
	v_lshlrev_b32_e32 v6, 2, v44
	v_mov_b32_e32 v7, v131
	v_lshl_add_u64 v[6:7], s[96:97], 0, v[6:7]
	v_lshlrev_b64 v[16:17], 12, v[34:35]
	v_lshl_add_u64 v[16:17], v[6:7], 0, v[16:17]
	global_store_dword v[16:17], v8, off nt
	v_lshlrev_b64 v[16:17], 12, v[4:5]
	v_lshl_add_u64 v[16:17], v[6:7], 0, v[16:17]
	global_store_dword v[16:17], v9, off nt
	v_lshlrev_b64 v[16:17], 12, v[2:3]
	v_lshl_add_u64 v[16:17], v[6:7], 0, v[16:17]
	global_store_dword v[16:17], v10, off nt
	v_lshlrev_b64 v[16:17], 12, v[0:1]
	v_lshl_add_u64 v[6:7], v[6:7], 0, v[16:17]
	global_store_dword v[6:7], v11, off nt

.LBB0_1681:
	s_or_b64 exec, exec, s[8:9]
	s_and_saveexec_b64 s[8:9], s[14:15]
	s_xor_b64 s[8:9], exec, s[8:9]
	s_cbranch_execz .LBB0_1685
	v_cvt_pk_bf16_f32 v0, v12, v13
	v_cvt_pk_bf16_f32 v1, v14, v15
	v_lshl_add_u64 v[2:3], v[64:65], 1, v[36:37]
	global_store_dwordx2 v[2:3], v[0:1], off offset:112
	s_and_saveexec_b64 s[12:13], s[6:7]
	s_cbranch_execz .LBB0_1684
	v_ashrrev_i32_e32 v33, 31, v32
	v_lshlrev_b32_e32 v130, 2, v44
	v_lshl_add_u64 v[0:1], s[28:29], 0, v[130:131]
	v_lshlrev_b64 v[2:3], 12, v[32:33]
	v_lshl_add_u64 v[2:3], v[0:1], 0, v[2:3]
	global_store_dword v[2:3], v12, off nt
	v_or_b32_e32 v2, 57, v64
	v_ashrrev_i32_e32 v3, 31, v2
	v_lshlrev_b64 v[2:3], 12, v[2:3]
	v_lshl_add_u64 v[2:3], v[0:1], 0, v[2:3]
	global_store_dword v[2:3], v13, off nt
	v_or_b32_e32 v2, 58, v64
	v_ashrrev_i32_e32 v3, 31, v2
	v_lshlrev_b64 v[2:3], 12, v[2:3]
	v_lshl_add_u64 v[2:3], v[0:1], 0, v[2:3]
	global_store_dword v[2:3], v14, off nt
	v_or_b32_e32 v2, 59, v64
	v_ashrrev_i32_e32 v3, 31, v2
	v_lshlrev_b64 v[2:3], 12, v[2:3]
	v_lshl_add_u64 v[0:1], v[0:1], 0, v[2:3]
	global_store_dword v[0:1], v15, off nt

.LBB0_1688:
	s_or_b64 exec, exec, s[12:13]
	v_or_b32_e32 v4, 57, v64
	v_or_b32_e32 v2, 58, v64
	v_or_b32_e32 v0, 59, v64
	s_mov_b64 s[10:11], -1
	s_andn2_b64 vcc, exec, s[36:37]
	v_ashrrev_i32_e32 v33, 31, v32
	v_ashrrev_i32_e32 v5, 31, v4
	v_ashrrev_i32_e32 v3, 31, v2
	v_ashrrev_i32_e32 v1, 31, v0
	s_cbranch_vccnz .LBB0_1692
	v_lshlrev_b32_e32 v6, 1, v44
	v_mov_b32_e32 v7, v131
	v_lshl_add_u64 v[6:7], s[0:1], 0, v[6:7]
	v_lshlrev_b64 v[8:9], 11, v[32:33]
	v_cvt_pk_bf16_f32 v10, v12, s0
	v_lshl_add_u64 v[8:9], v[6:7], 0, v[8:9]
	global_store_short v[8:9], v10, off
	v_lshlrev_b64 v[8:9], 11, v[4:5]
	v_cvt_pk_bf16_f32 v10, v13, s0
	v_lshl_add_u64 v[8:9], v[6:7], 0, v[8:9]
	global_store_short v[8:9], v10, off
	v_lshlrev_b64 v[8:9], 11, v[2:3]
	v_cvt_pk_bf16_f32 v10, v14, s0
	v_lshl_add_u64 v[8:9], v[6:7], 0, v[8:9]
	global_store_short v[8:9], v10, off
	v_lshlrev_b64 v[8:9], 11, v[0:1]
	v_cvt_pk_bf16_f32 v10, v15, s0
	v_lshl_add_u64 v[6:7], v[6:7], 0, v[8:9]
	global_store_short v[6:7], v10, off
	s_and_saveexec_b64 s[10:11], s[6:7]
	s_cbranch_execz .LBB0_1691
	v_lshlrev_b32_e32 v6, 2, v44
	v_mov_b32_e32 v7, v131
	v_lshl_add_u64 v[6:7], s[96:97], 0, v[6:7]
	v_lshlrev_b64 v[8:9], 12, v[32:33]
	v_lshl_add_u64 v[8:9], v[6:7], 0, v[8:9]
	global_store_dword v[8:9], v12, off nt
	v_lshlrev_b64 v[8:9], 12, v[4:5]
	v_lshl_add_u64 v[8:9], v[6:7], 0, v[8:9]
	global_store_dword v[8:9], v13, off nt
	v_lshlrev_b64 v[8:9], 12, v[2:3]
	v_lshl_add_u64 v[8:9], v[6:7], 0, v[8:9]
	global_store_dword v[8:9], v14, off nt
	v_lshlrev_b64 v[8:9], 12, v[0:1]
	v_lshl_add_u64 v[6:7], v[6:7], 0, v[8:9]
	global_store_dword v[6:7], v15, off nt

.LBB0_1695:
	v_lshlrev_b32_e32 v66, 1, v74
	v_mov_b32_e32 v67, v131
	v_lshl_add_u64 v[76:77], s[0:1], 0, v[66:67]
	v_lshlrev_b64 v[66:67], 11, v[64:65]
	v_cvt_pk_bf16_f32 v70, v48, s0
	v_lshl_add_u64 v[66:67], v[76:77], 0, v[66:67]
	global_store_short v[66:67], v70, off
	v_or_b32_e32 v66, 1, v64
	v_ashrrev_i32_e32 v67, 31, v66
	v_lshlrev_b64 v[70:71], 11, v[66:67]
	v_cvt_pk_bf16_f32 v72, v49, s0
	v_lshl_add_u64 v[70:71], v[76:77], 0, v[70:71]
	global_store_short v[70:71], v72, off
	v_or_b32_e32 v70, 2, v64
	v_ashrrev_i32_e32 v71, 31, v70
	v_lshlrev_b64 v[72:73], 11, v[70:71]
	v_cvt_pk_bf16_f32 v78, v50, s0
	v_lshl_add_u64 v[72:73], v[76:77], 0, v[72:73]
	global_store_short v[72:73], v78, off
	v_or_b32_e32 v72, 3, v64
	v_ashrrev_i32_e32 v73, 31, v72
	v_lshlrev_b64 v[78:79], 11, v[72:73]
	v_cvt_pk_bf16_f32 v80, v51, s0
	v_lshl_add_u64 v[76:77], v[76:77], 0, v[78:79]
	global_store_short v[76:77], v80, off
	s_and_saveexec_b64 s[10:11], s[8:9]
	s_cbranch_execz .LBB0_1697
	v_lshlrev_b32_e32 v76, 2, v74
	v_mov_b32_e32 v77, v131
	v_lshl_add_u64 v[76:77], s[96:97], 0, v[76:77]
	v_lshlrev_b64 v[66:67], 12, v[66:67]
	v_lshl_add_u64 v[66:67], v[76:77], 0, v[66:67]
	global_store_dword v[66:67], v49, off nt
	v_lshlrev_b64 v[66:67], 12, v[70:71]
	v_lshl_add_u64 v[66:67], v[76:77], 0, v[66:67]
	v_lshlrev_b64 v[78:79], 12, v[64:65]
	global_store_dword v[66:67], v50, off nt
	v_lshlrev_b64 v[66:67], 12, v[72:73]
	v_lshl_add_u64 v[78:79], v[76:77], 0, v[78:79]
	v_lshl_add_u64 v[66:67], v[76:77], 0, v[66:67]
	global_store_dword v[78:79], v48, off nt
	global_store_dword v[66:67], v51, off nt

.LBB0_1699:
	v_lshlrev_b32_e32 v48, 1, v74
	v_mov_b32_e32 v49, v131
	v_ashrrev_i32_e32 v67, 31, v66
	v_lshl_add_u64 v[72:73], s[0:1], 0, v[48:49]
	v_lshlrev_b64 v[48:49], 11, v[66:67]
	v_cvt_pk_bf16_f32 v50, v52, s0
	v_lshl_add_u64 v[48:49], v[72:73], 0, v[48:49]
	global_store_short v[48:49], v50, off
	v_or_b32_e32 v48, 9, v64
	v_ashrrev_i32_e32 v49, 31, v48
	v_lshlrev_b64 v[50:51], 11, v[48:49]
	v_cvt_pk_bf16_f32 v70, v53, s0
	v_lshl_add_u64 v[50:51], v[72:73], 0, v[50:51]
	global_store_short v[50:51], v70, off
	v_or_b32_e32 v50, 10, v64
	v_ashrrev_i32_e32 v51, 31, v50
	v_lshlrev_b64 v[70:71], 11, v[50:51]
	v_cvt_pk_bf16_f32 v76, v54, s0
	v_lshl_add_u64 v[70:71], v[72:73], 0, v[70:71]
	global_store_short v[70:71], v76, off
	v_or_b32_e32 v70, 11, v64
	v_ashrrev_i32_e32 v71, 31, v70
	v_lshlrev_b64 v[76:77], 11, v[70:71]
	v_cvt_pk_bf16_f32 v78, v55, s0
	v_lshl_add_u64 v[72:73], v[72:73], 0, v[76:77]
	global_store_short v[72:73], v78, off
	s_and_saveexec_b64 s[10:11], s[8:9]
	s_cbranch_execz .LBB0_1701
	v_lshlrev_b32_e32 v72, 2, v74
	v_mov_b32_e32 v73, v131
	v_lshl_add_u64 v[72:73], s[96:97], 0, v[72:73]
	v_lshlrev_b64 v[48:49], 12, v[48:49]
	v_lshl_add_u64 v[48:49], v[72:73], 0, v[48:49]
	global_store_dword v[48:49], v53, off nt
	v_lshlrev_b64 v[48:49], 12, v[50:51]
	v_lshl_add_u64 v[48:49], v[72:73], 0, v[48:49]
	v_lshlrev_b64 v[76:77], 12, v[66:67]
	global_store_dword v[48:49], v54, off nt
	v_lshlrev_b64 v[48:49], 12, v[70:71]
	v_lshl_add_u64 v[76:77], v[72:73], 0, v[76:77]
	v_lshl_add_u64 v[48:49], v[72:73], 0, v[48:49]
	global_store_dword v[76:77], v52, off nt
	global_store_dword v[48:49], v55, off nt

.LBB0_1703:
	v_lshlrev_b32_e32 v48, 1, v74
	v_mov_b32_e32 v49, v131
	v_ashrrev_i32_e32 v55, 31, v54
	v_lshl_add_u64 v[70:71], s[0:1], 0, v[48:49]
	v_lshlrev_b64 v[48:49], 11, v[54:55]
	v_cvt_pk_bf16_f32 v50, v56, s0
	v_lshl_add_u64 v[48:49], v[70:71], 0, v[48:49]
	global_store_short v[48:49], v50, off
	v_or_b32_e32 v48, 17, v64
	v_ashrrev_i32_e32 v49, 31, v48
	v_lshlrev_b64 v[50:51], 11, v[48:49]
	v_cvt_pk_bf16_f32 v52, v57, s0
	v_lshl_add_u64 v[50:51], v[70:71], 0, v[50:51]
	global_store_short v[50:51], v52, off
	v_or_b32_e32 v50, 18, v64
	v_ashrrev_i32_e32 v51, 31, v50
	v_lshlrev_b64 v[52:53], 11, v[50:51]
	v_cvt_pk_bf16_f32 v67, v58, s0
	v_lshl_add_u64 v[52:53], v[70:71], 0, v[52:53]
	global_store_short v[52:53], v67, off
	v_or_b32_e32 v52, 19, v64
	v_ashrrev_i32_e32 v53, 31, v52
	v_lshlrev_b64 v[72:73], 11, v[52:53]
	v_cvt_pk_bf16_f32 v67, v59, s0
	v_lshl_add_u64 v[70:71], v[70:71], 0, v[72:73]
	global_store_short v[70:71], v67, off
	s_and_saveexec_b64 s[10:11], s[8:9]
	s_cbranch_execz .LBB0_1705
	v_lshlrev_b32_e32 v70, 2, v74
	v_mov_b32_e32 v71, v131
	v_lshl_add_u64 v[70:71], s[96:97], 0, v[70:71]
	v_lshlrev_b64 v[48:49], 12, v[48:49]
	v_lshl_add_u64 v[48:49], v[70:71], 0, v[48:49]
	global_store_dword v[48:49], v57, off nt
	v_lshlrev_b64 v[48:49], 12, v[50:51]
	v_lshl_add_u64 v[48:49], v[70:71], 0, v[48:49]
	v_lshlrev_b64 v[72:73], 12, v[54:55]
	global_store_dword v[48:49], v58, off nt
	v_lshlrev_b64 v[48:49], 12, v[52:53]
	v_lshl_add_u64 v[72:73], v[70:71], 0, v[72:73]
	v_lshl_add_u64 v[48:49], v[70:71], 0, v[48:49]
	global_store_dword v[72:73], v56, off nt
	global_store_dword v[48:49], v59, off nt

.LBB0_1707:
	v_lshlrev_b32_e32 v48, 1, v74
	v_mov_b32_e32 v49, v131
	v_ashrrev_i32_e32 v53, 31, v52
	v_lshl_add_u64 v[58:59], s[0:1], 0, v[48:49]
	v_lshlrev_b64 v[48:49], 11, v[52:53]
	v_cvt_pk_bf16_f32 v50, v60, s0
	v_lshl_add_u64 v[48:49], v[58:59], 0, v[48:49]
	global_store_short v[48:49], v50, off
	v_or_b32_e32 v48, 25, v64
	v_ashrrev_i32_e32 v49, 31, v48
	v_lshlrev_b64 v[50:51], 11, v[48:49]
	v_cvt_pk_bf16_f32 v55, v61, s0
	v_lshl_add_u64 v[50:51], v[58:59], 0, v[50:51]
	global_store_short v[50:51], v55, off
	v_or_b32_e32 v50, 26, v64
	v_ashrrev_i32_e32 v51, 31, v50
	v_lshlrev_b64 v[56:57], 11, v[50:51]
	v_cvt_pk_bf16_f32 v55, v62, s0
	v_lshl_add_u64 v[56:57], v[58:59], 0, v[56:57]
	global_store_short v[56:57], v55, off
	v_or_b32_e32 v56, 27, v64
	v_ashrrev_i32_e32 v57, 31, v56
	v_lshlrev_b64 v[70:71], 11, v[56:57]
	v_cvt_pk_bf16_f32 v55, v63, s0
	v_lshl_add_u64 v[58:59], v[58:59], 0, v[70:71]
	global_store_short v[58:59], v55, off
	s_and_saveexec_b64 s[10:11], s[8:9]
	s_cbranch_execz .LBB0_1709
	v_lshlrev_b32_e32 v58, 2, v74
	v_mov_b32_e32 v59, v131
	v_lshl_add_u64 v[58:59], s[96:97], 0, v[58:59]
	v_lshlrev_b64 v[48:49], 12, v[48:49]
	v_lshl_add_u64 v[48:49], v[58:59], 0, v[48:49]
	global_store_dword v[48:49], v61, off nt
	v_lshlrev_b64 v[48:49], 12, v[50:51]
	v_lshl_add_u64 v[48:49], v[58:59], 0, v[48:49]
	v_lshlrev_b64 v[70:71], 12, v[52:53]
	global_store_dword v[48:49], v62, off nt
	v_lshlrev_b64 v[48:49], 12, v[56:57]
	v_lshl_add_u64 v[70:71], v[58:59], 0, v[70:71]
	v_lshl_add_u64 v[48:49], v[58:59], 0, v[48:49]
	global_store_dword v[70:71], v60, off nt
	global_store_dword v[48:49], v63, off nt

.LBB0_1711:
	v_lshlrev_b32_e32 v48, 1, v74
	v_mov_b32_e32 v49, v131
	v_ashrrev_i32_e32 v51, 31, v50
	v_lshl_add_u64 v[60:61], s[0:1], 0, v[48:49]
	v_lshlrev_b64 v[48:49], 11, v[50:51]
	v_cvt_pk_bf16_f32 v53, v32, s0
	v_lshl_add_u64 v[48:49], v[60:61], 0, v[48:49]
	global_store_short v[48:49], v53, off
	v_or_b32_e32 v48, 33, v64
	v_ashrrev_i32_e32 v49, 31, v48
	v_lshlrev_b64 v[56:57], 11, v[48:49]
	v_cvt_pk_bf16_f32 v53, v33, s0
	v_lshl_add_u64 v[56:57], v[60:61], 0, v[56:57]
	global_store_short v[56:57], v53, off
	v_or_b32_e32 v56, 34, v64
	v_ashrrev_i32_e32 v57, 31, v56
	v_lshlrev_b64 v[58:59], 11, v[56:57]
	v_cvt_pk_bf16_f32 v53, v34, s0
	v_lshl_add_u64 v[58:59], v[60:61], 0, v[58:59]
	global_store_short v[58:59], v53, off
	v_or_b32_e32 v58, 35, v64
	v_ashrrev_i32_e32 v59, 31, v58
	v_lshlrev_b64 v[62:63], 11, v[58:59]
	v_cvt_pk_bf16_f32 v53, v35, s0
	v_lshl_add_u64 v[60:61], v[60:61], 0, v[62:63]
	global_store_short v[60:61], v53, off
	s_and_saveexec_b64 s[42:43], s[6:7]
	s_cbranch_execz .LBB0_1713
	v_lshlrev_b32_e32 v60, 2, v74
	v_mov_b32_e32 v61, v131
	v_lshl_add_u64 v[60:61], s[96:97], 0, v[60:61]
	v_lshlrev_b64 v[48:49], 12, v[48:49]
	v_lshl_add_u64 v[48:49], v[60:61], 0, v[48:49]
	global_store_dword v[48:49], v33, off nt
	v_lshlrev_b64 v[48:49], 12, v[56:57]
	v_lshl_add_u64 v[48:49], v[60:61], 0, v[48:49]
	v_lshlrev_b64 v[62:63], 12, v[50:51]
	global_store_dword v[48:49], v34, off nt
	v_lshlrev_b64 v[48:49], 12, v[58:59]
	v_lshl_add_u64 v[62:63], v[60:61], 0, v[62:63]
	v_lshl_add_u64 v[48:49], v[60:61], 0, v[48:49]
	global_store_dword v[62:63], v32, off nt
	global_store_dword v[48:49], v35, off nt

.LBB0_1715:
	v_lshlrev_b32_e32 v32, 1, v74
	v_mov_b32_e32 v33, v131
	v_ashrrev_i32_e32 v49, 31, v48
	v_lshl_add_u64 v[58:59], s[0:1], 0, v[32:33]
	v_lshlrev_b64 v[32:33], 11, v[48:49]
	v_cvt_pk_bf16_f32 v34, v36, s0
	v_lshl_add_u64 v[32:33], v[58:59], 0, v[32:33]
	global_store_short v[32:33], v34, off
	v_or_b32_e32 v32, 41, v64
	v_ashrrev_i32_e32 v33, 31, v32
	v_lshlrev_b64 v[34:35], 11, v[32:33]
	v_cvt_pk_bf16_f32 v51, v37, s0
	v_lshl_add_u64 v[34:35], v[58:59], 0, v[34:35]
	global_store_short v[34:35], v51, off
	v_or_b32_e32 v34, 42, v64
	v_ashrrev_i32_e32 v35, 31, v34
	v_lshlrev_b64 v[56:57], 11, v[34:35]
	v_cvt_pk_bf16_f32 v51, v38, s0
	v_lshl_add_u64 v[56:57], v[58:59], 0, v[56:57]
	global_store_short v[56:57], v51, off
	v_or_b32_e32 v56, 43, v64
	v_ashrrev_i32_e32 v57, 31, v56
	v_lshlrev_b64 v[60:61], 11, v[56:57]
	v_cvt_pk_bf16_f32 v51, v39, s0
	v_lshl_add_u64 v[58:59], v[58:59], 0, v[60:61]
	global_store_short v[58:59], v51, off
	s_and_saveexec_b64 s[42:43], s[6:7]
	s_cbranch_execz .LBB0_1717
	v_lshlrev_b32_e32 v58, 2, v74
	v_mov_b32_e32 v59, v131
	v_lshl_add_u64 v[58:59], s[96:97], 0, v[58:59]
	v_lshlrev_b64 v[32:33], 12, v[32:33]
	v_lshl_add_u64 v[32:33], v[58:59], 0, v[32:33]
	global_store_dword v[32:33], v37, off nt
	v_lshlrev_b64 v[32:33], 12, v[34:35]
	v_lshl_add_u64 v[32:33], v[58:59], 0, v[32:33]
	v_lshlrev_b64 v[60:61], 12, v[48:49]
	global_store_dword v[32:33], v38, off nt
	v_lshlrev_b64 v[32:33], 12, v[56:57]
	v_lshl_add_u64 v[60:61], v[58:59], 0, v[60:61]
	v_lshl_add_u64 v[32:33], v[58:59], 0, v[32:33]
	global_store_dword v[60:61], v36, off nt
	global_store_dword v[32:33], v39, off nt

.LBB0_1719:
	v_lshlrev_b32_e32 v32, 1, v74
	v_mov_b32_e32 v33, v131
	v_ashrrev_i32_e32 v35, 31, v34
	v_lshl_add_u64 v[56:57], s[0:1], 0, v[32:33]
	v_lshlrev_b64 v[32:33], 11, v[34:35]
	v_cvt_pk_bf16_f32 v36, v40, s0
	v_lshl_add_u64 v[32:33], v[56:57], 0, v[32:33]
	global_store_short v[32:33], v36, off
	v_or_b32_e32 v32, 49, v64
	v_ashrrev_i32_e32 v33, 31, v32
	v_lshlrev_b64 v[36:37], 11, v[32:33]
	v_cvt_pk_bf16_f32 v38, v41, s0
	v_lshl_add_u64 v[36:37], v[56:57], 0, v[36:37]
	global_store_short v[36:37], v38, off
	v_or_b32_e32 v36, 50, v64
	v_ashrrev_i32_e32 v37, 31, v36
	v_lshlrev_b64 v[38:39], 11, v[36:37]
	v_cvt_pk_bf16_f32 v49, v42, s0
	v_lshl_add_u64 v[38:39], v[56:57], 0, v[38:39]
	global_store_short v[38:39], v49, off
	v_or_b32_e32 v38, 51, v64
	v_ashrrev_i32_e32 v39, 31, v38
	v_lshlrev_b64 v[58:59], 11, v[38:39]
	v_cvt_pk_bf16_f32 v49, v43, s0
	v_lshl_add_u64 v[56:57], v[56:57], 0, v[58:59]
	global_store_short v[56:57], v49, off
	s_and_saveexec_b64 s[42:43], s[6:7]
	s_cbranch_execz .LBB0_1721
	v_lshlrev_b32_e32 v56, 2, v74
	v_mov_b32_e32 v57, v131
	v_lshl_add_u64 v[56:57], s[96:97], 0, v[56:57]
	v_lshlrev_b64 v[32:33], 12, v[32:33]
	v_lshl_add_u64 v[32:33], v[56:57], 0, v[32:33]
	global_store_dword v[32:33], v41, off nt
	v_lshlrev_b64 v[32:33], 12, v[36:37]
	v_lshl_add_u64 v[32:33], v[56:57], 0, v[32:33]
	v_lshlrev_b64 v[58:59], 12, v[34:35]
	global_store_dword v[32:33], v42, off nt
	v_lshlrev_b64 v[32:33], 12, v[38:39]
	v_lshl_add_u64 v[58:59], v[56:57], 0, v[58:59]
	v_lshl_add_u64 v[32:33], v[56:57], 0, v[32:33]
	global_store_dword v[58:59], v40, off nt
	global_store_dword v[32:33], v43, off nt

.LBB0_1723:
	v_lshlrev_b32_e32 v36, 1, v74
	v_mov_b32_e32 v37, v131
	v_ashrrev_i32_e32 v33, 31, v32
	v_lshl_add_u64 v[42:43], s[0:1], 0, v[36:37]
	v_lshlrev_b64 v[36:37], 11, v[32:33]
	v_cvt_pk_bf16_f32 v35, v44, s0
	v_lshl_add_u64 v[36:37], v[42:43], 0, v[36:37]
	global_store_short v[36:37], v35, off
	v_or_b32_e32 v36, 57, v64
	v_ashrrev_i32_e32 v37, 31, v36
	v_lshlrev_b64 v[38:39], 11, v[36:37]
	v_cvt_pk_bf16_f32 v35, v45, s0
	v_lshl_add_u64 v[38:39], v[42:43], 0, v[38:39]
	global_store_short v[38:39], v35, off
	v_or_b32_e32 v38, 58, v64
	v_ashrrev_i32_e32 v39, 31, v38
	v_lshlrev_b64 v[40:41], 11, v[38:39]
	v_cvt_pk_bf16_f32 v35, v46, s0
	v_lshl_add_u64 v[40:41], v[42:43], 0, v[40:41]
	global_store_short v[40:41], v35, off
	v_or_b32_e32 v40, 59, v64
	v_ashrrev_i32_e32 v41, 31, v40
	v_lshlrev_b64 v[56:57], 11, v[40:41]
	v_cvt_pk_bf16_f32 v35, v47, s0
	v_lshl_add_u64 v[42:43], v[42:43], 0, v[56:57]
	global_store_short v[42:43], v35, off
	s_and_saveexec_b64 s[38:39], s[6:7]
	s_cbranch_execz .LBB0_1725
	v_lshlrev_b32_e32 v42, 2, v74
	v_mov_b32_e32 v43, v131
	v_lshl_add_u64 v[42:43], s[96:97], 0, v[42:43]
	v_lshlrev_b64 v[36:37], 12, v[36:37]
	v_lshl_add_u64 v[36:37], v[42:43], 0, v[36:37]
	global_store_dword v[36:37], v45, off nt
	v_lshlrev_b64 v[36:37], 12, v[38:39]
	v_lshl_add_u64 v[36:37], v[42:43], 0, v[36:37]
	v_lshlrev_b64 v[56:57], 12, v[32:33]
	global_store_dword v[36:37], v46, off nt
	v_lshlrev_b64 v[36:37], 12, v[40:41]
	v_lshl_add_u64 v[56:57], v[42:43], 0, v[56:57]
	v_lshl_add_u64 v[36:37], v[42:43], 0, v[36:37]
	global_store_dword v[56:57], v44, off nt
	global_store_dword v[36:37], v47, off nt
